# conv edge fix-up folded into the start of the down-GEMM phase (each workgroup repairs the edge rows of its own A tile), removing one phase and one grid barrier per layer
# speedup vs baseline: 1.0012x; 1.0012x over previous
.LBB0_1038:
	s_cmp_gt_i32 s72, 10
	s_cselect_b64 s[4:5], -1, 0
	s_cmp_lt_i32 s73, 11
	s_cselect_b64 s[6:7], -1, 0
	s_or_b64 s[4:5], s[4:5], s[6:7]
	v_readlane_b32 s2, v254, 47
	s_and_b64 vcc, exec, s[4:5]
	v_readlane_b32 s3, v254, 48
	s_cbranch_vccnz .LBB0_1097
	s_branch .LBB0_1097
	v_mov_b32_e32 v0, v230
	v_readlane_b32 s0, v254, 55
	s_nop 1
	v_add_u32_e32 v160, s0, v0
	s_mov_b32 s0, 0x58000
	v_cmp_gt_i32_e32 vcc, s0, v160
	s_and_saveexec_b64 s[6:7], vcc
	s_cbranch_execz .LBB0_1046
	s_add_u32 s8, s70, 0x3b00000
	s_addc_u32 s9, s71, 0
	s_add_u32 s10, s70, 0xbf00000
	v_readlane_b32 s52, v254, 3
	s_addc_u32 s11, s71, 0
	v_readlane_b32 s56, v254, 7
	v_readlane_b32 s57, v254, 8
	s_add_u32 s12, s56, 0x2c00
	v_readlane_b32 s54, v254, 5
	s_addc_u32 s13, s57, 0
	v_readlane_b32 s55, v254, 6
	s_add_u32 s14, s54, 0x2c00
	s_addc_u32 s15, s55, 0
	s_add_u32 s16, s54, 0x5800
	s_addc_u32 s17, s55, 0
	s_add_u32 s34, s54, 0x8400
	s_addc_u32 s35, s55, 0
	s_add_u32 s48, s54, 0xb000
	s_addc_u32 s49, s55, 0
	v_readlane_b32 s58, v254, 9
	s_add_u32 s54, s54, 0xdc00
	v_lshlrev_b32_e32 v0, 3, v0
	s_addc_u32 s55, s55, 0
	v_lshl_add_u32 v161, s84, 12, v0
	s_lshl_b32 s0, s97, 3
	s_mov_b64 s[56:57], 0
	s_movk_i32 s20, 0x2c00
	s_movk_i32 s21, 0x3f8
	v_mov_b64_e32 v[136:137], s[8:9]
	s_mov_b32 s58, 0xbfb8aa3b
	s_movk_i32 s30, 0x1600
	s_mov_b32 s31, 0x57fff
	v_readlane_b32 s53, v254, 4
	v_readlane_b32 s59, v254, 10
	s_branch .LBB0_1042

.LBB0_1097:
	s_add_u32 s12, s70, 0x110000
	s_addc_u32 s13, s71, 0
	s_cmp_lt_i32 s72, 12
	s_cselect_b64 s[14:15], -1, 0
	s_cmp_gt_i32 s73, 11
	s_cselect_b64 s[4:5], -1, 0
	s_and_b64 s[4:5], s[14:15], s[4:5]
	s_and_b64 vcc, exec, s[4:5]
	s_mov_b64 s[28:29], s[84:85]
	s_cbranch_vccz .LBB0_1148
	s_cmpk_gt_i32 s84, 0xff
	s_cbranch_scc1 .LfxA_done
	s_and_b32 s6, s84, 7
	s_lshl_b32 s6, s6, 3
	s_bfe_u32 s7, s84, 0x30003
	s_add_i32 s4, s6, s7
	s_sub_i32 s4, s4, 32
	s_cmp_lt_i32 s4, 0
	s_cbranch_scc1 .LfxA_done
	s_and_b32 s6, s4, 3
	s_cmp_lg_u32 s6, 0
	s_cselect_b32 s20, 1, 0
	s_cmp_lg_u32 s6, 3
	s_cselect_b32 s21, 1, 0
	s_add_u32 s8, s70, 0x5b00000
	s_addc_u32 s9, s71, 0
	v_readlane_b32 s10, v254, 5
	v_readlane_b32 s11, v254, 6
	s_nop 0
	s_mul_i32 s6, s4, 0x16000
	s_add_i32 s6, s6, 0x5800
	s_add_u32 s60, s8, s6
	s_addc_u32 s61, s9, 0
	s_add_i32 s6, s4, -1
	s_mul_i32 s6, s6, 0x16000
	s_add_i32 s6, s6, 0xb000
	s_add_u32 s62, s8, s6
	s_addc_u32 s63, s9, 0
	s_add_u32 s64, s10, 0x0
	s_addc_u32 s65, s11, 0
	s_lshl_b32 s6, s4, 8
	s_mul_i32 s6, s6, 0x1600
	s_add_u32 s6, s6, 0xbf00000
	s_add_u32 s66, s70, s6
	s_addc_u32 s67, s71, 0
	s_mul_i32 s6, s4, 0x16000
	s_add_i32 s6, s6, 0x10800
	s_add_u32 s86, s8, s6
	s_addc_u32 s87, s9, 0
	s_add_i32 s6, s4, 1
	s_mul_i32 s6, s6, 0x16000
	s_add_u32 s88, s8, s6
	s_addc_u32 s89, s9, 0
	s_add_u32 s90, s10, 0xb000
	s_addc_u32 s91, s11, 0
	s_lshl_b32 s6, s4, 8
	s_add_i32 s6, s6, 255
	s_mul_i32 s6, s6, 0x1600
	s_add_u32 s6, s6, 0xbf00000
	s_add_u32 s92, s70, s6
	s_addc_u32 s93, s71, 0
	v_readfirstlane_b32 s7, v230
	s_cmpk_lt_u32 s7, 0x180
	s_cselect_b32 s5, 1, 0
	v_lshlrev_b32_e32 v172, 3, v230
	v_add_u32_e32 v173, 0x1000, v172
	v_add_u32_e32 v174, 0x2000, v172
	v_add_u32_e32 v175, 0x2c00, v172
	v_add_u32_e32 v176, 0x2c00, v173
	v_add_u32_e32 v177, 0x2c00, v174
	v_lshlrev_b32_e32 v178, 2, v230
	v_add_u32_e32 v179, 0x800, v178
	v_add_u32_e32 v180, 0x1000, v178
	s_cmp_eq_u32 s20, 0
	s_cbranch_scc1 .LfxA_L0
	global_load_dwordx2 v[100:101], v172, s[60:61]
	global_load_dwordx2 v[102:103], v175, s[60:61]
	global_load_dwordx2 v[104:105], v172, s[62:63]
	global_load_dwordx2 v[106:107], v175, s[62:63]
	global_load_dwordx2 v[108:109], v172, s[64:65]
	global_load_dwordx2 v[110:111], v175, s[64:65]
	global_load_dwordx2 v[112:113], v173, s[60:61]
	global_load_dwordx2 v[114:115], v176, s[60:61]
	global_load_dwordx2 v[116:117], v173, s[62:63]
	global_load_dwordx2 v[118:119], v176, s[62:63]
	global_load_dwordx2 v[120:121], v173, s[64:65]
	global_load_dwordx2 v[122:123], v176, s[64:65]
	s_cmp_eq_u32 s5, 0
	s_cbranch_scc1 .LfxA_L0
	global_load_dwordx2 v[124:125], v174, s[60:61]
	global_load_dwordx2 v[126:127], v177, s[60:61]
	global_load_dwordx2 v[128:129], v174, s[62:63]
	global_load_dwordx2 v[130:131], v177, s[62:63]
	global_load_dwordx2 v[132:133], v174, s[64:65]
	global_load_dwordx2 v[134:135], v177, s[64:65]
.LfxA_L0:
	s_cmp_eq_u32 s21, 0
	s_cbranch_scc1 .LfxA_L1
	global_load_dwordx2 v[136:137], v172, s[86:87]
	global_load_dwordx2 v[138:139], v175, s[86:87]
	global_load_dwordx2 v[140:141], v172, s[88:89]
	global_load_dwordx2 v[142:143], v175, s[88:89]
	global_load_dwordx2 v[144:145], v172, s[90:91]
	global_load_dwordx2 v[146:147], v175, s[90:91]
	global_load_dwordx2 v[148:149], v173, s[86:87]
	global_load_dwordx2 v[150:151], v176, s[86:87]
	global_load_dwordx2 v[152:153], v173, s[88:89]
	global_load_dwordx2 v[154:155], v176, s[88:89]
	global_load_dwordx2 v[156:157], v173, s[90:91]
	global_load_dwordx2 v[158:159], v176, s[90:91]
	s_cmp_eq_u32 s5, 0
	s_cbranch_scc1 .LfxA_L1
	global_load_dwordx2 v[160:161], v174, s[86:87]
	global_load_dwordx2 v[162:163], v177, s[86:87]
	global_load_dwordx2 v[164:165], v174, s[88:89]
	global_load_dwordx2 v[166:167], v177, s[88:89]
	global_load_dwordx2 v[168:169], v174, s[90:91]
	global_load_dwordx2 v[170:171], v177, s[90:91]
.LfxA_L1:
	s_waitcnt vmcnt(0)
	s_cmp_eq_u32 s20, 0
	s_cbranch_scc1 .LfxA_C0
	v_fmac_f32_e32 v100, v108, v104
	v_fmac_f32_e32 v101, v109, v105
	v_fmac_f32_e32 v102, v110, v106
	v_fmac_f32_e32 v103, v111, v107
	v_mul_f32_e32 v181, 0xbfb8aa3b, v100
	v_mul_f32_e32 v182, 0xbfb8aa3b, v101
	v_exp_f32_e32 v181, v181
	v_exp_f32_e32 v182, v182
	s_nop 0
	v_add_f32_e32 v181, 1.0, v181
	v_add_f32_e32 v182, 1.0, v182
	v_rcp_f32_e32 v181, v181
	v_rcp_f32_e32 v182, v182
	s_nop 0
	v_mul_f32_e32 v100, v100, v181
	v_mul_f32_e32 v101, v101, v182
	v_mul_f32_e32 v100, v100, v102
	v_mul_f32_e32 v101, v101, v103
	v_cvt_pk_bf16_f32 v100, v100, v101
	global_store_dword v178, v100, s[66:67]
	v_fmac_f32_e32 v112, v120, v116
	v_fmac_f32_e32 v113, v121, v117
	v_fmac_f32_e32 v114, v122, v118
	v_fmac_f32_e32 v115, v123, v119
	v_mul_f32_e32 v181, 0xbfb8aa3b, v112
	v_mul_f32_e32 v182, 0xbfb8aa3b, v113
	v_exp_f32_e32 v181, v181
	v_exp_f32_e32 v182, v182
	s_nop 0
	v_add_f32_e32 v181, 1.0, v181
	v_add_f32_e32 v182, 1.0, v182
	v_rcp_f32_e32 v181, v181
	v_rcp_f32_e32 v182, v182
	s_nop 0
	v_mul_f32_e32 v112, v112, v181
	v_mul_f32_e32 v113, v113, v182
	v_mul_f32_e32 v112, v112, v114
	v_mul_f32_e32 v113, v113, v115
	v_cvt_pk_bf16_f32 v112, v112, v113
	global_store_dword v179, v112, s[66:67]
	s_cmp_eq_u32 s5, 0
	s_cbranch_scc1 .LfxA_C0
	v_fmac_f32_e32 v124, v132, v128
	v_fmac_f32_e32 v125, v133, v129
	v_fmac_f32_e32 v126, v134, v130
	v_fmac_f32_e32 v127, v135, v131
	v_mul_f32_e32 v181, 0xbfb8aa3b, v124
	v_mul_f32_e32 v182, 0xbfb8aa3b, v125
	v_exp_f32_e32 v181, v181
	v_exp_f32_e32 v182, v182
	s_nop 0
	v_add_f32_e32 v181, 1.0, v181
	v_add_f32_e32 v182, 1.0, v182
	v_rcp_f32_e32 v181, v181
	v_rcp_f32_e32 v182, v182
	s_nop 0
	v_mul_f32_e32 v124, v124, v181
	v_mul_f32_e32 v125, v125, v182
	v_mul_f32_e32 v124, v124, v126
	v_mul_f32_e32 v125, v125, v127
	v_cvt_pk_bf16_f32 v124, v124, v125
	global_store_dword v180, v124, s[66:67]
.LfxA_C0:
	s_cmp_eq_u32 s21, 0
	s_cbranch_scc1 .LfxA_C1
	v_fmac_f32_e32 v136, v144, v140
	v_fmac_f32_e32 v137, v145, v141
	v_fmac_f32_e32 v138, v146, v142
	v_fmac_f32_e32 v139, v147, v143
	v_mul_f32_e32 v181, 0xbfb8aa3b, v136
	v_mul_f32_e32 v182, 0xbfb8aa3b, v137
	v_exp_f32_e32 v181, v181
	v_exp_f32_e32 v182, v182
	s_nop 0
	v_add_f32_e32 v181, 1.0, v181
	v_add_f32_e32 v182, 1.0, v182
	v_rcp_f32_e32 v181, v181
	v_rcp_f32_e32 v182, v182
	s_nop 0
	v_mul_f32_e32 v136, v136, v181
	v_mul_f32_e32 v137, v137, v182
	v_mul_f32_e32 v136, v136, v138
	v_mul_f32_e32 v137, v137, v139
	v_cvt_pk_bf16_f32 v136, v136, v137
	global_store_dword v178, v136, s[92:93]
	v_fmac_f32_e32 v148, v156, v152
	v_fmac_f32_e32 v149, v157, v153
	v_fmac_f32_e32 v150, v158, v154
	v_fmac_f32_e32 v151, v159, v155
	v_mul_f32_e32 v181, 0xbfb8aa3b, v148
	v_mul_f32_e32 v182, 0xbfb8aa3b, v149
	v_exp_f32_e32 v181, v181
	v_exp_f32_e32 v182, v182
	s_nop 0
	v_add_f32_e32 v181, 1.0, v181
	v_add_f32_e32 v182, 1.0, v182
	v_rcp_f32_e32 v181, v181
	v_rcp_f32_e32 v182, v182
	s_nop 0
	v_mul_f32_e32 v148, v148, v181
	v_mul_f32_e32 v149, v149, v182
	v_mul_f32_e32 v148, v148, v150
	v_mul_f32_e32 v149, v149, v151
	v_cvt_pk_bf16_f32 v148, v148, v149
	global_store_dword v179, v148, s[92:93]
	s_cmp_eq_u32 s5, 0
	s_cbranch_scc1 .LfxA_C1
	v_fmac_f32_e32 v160, v168, v164
	v_fmac_f32_e32 v161, v169, v165
	v_fmac_f32_e32 v162, v170, v166
	v_fmac_f32_e32 v163, v171, v167
	v_mul_f32_e32 v181, 0xbfb8aa3b, v160
	v_mul_f32_e32 v182, 0xbfb8aa3b, v161
	v_exp_f32_e32 v181, v181
	v_exp_f32_e32 v182, v182
	s_nop 0
	v_add_f32_e32 v181, 1.0, v181
	v_add_f32_e32 v182, 1.0, v182
	v_rcp_f32_e32 v181, v181
	v_rcp_f32_e32 v182, v182
	s_nop 0
	v_mul_f32_e32 v160, v160, v181
	v_mul_f32_e32 v161, v161, v182
	v_mul_f32_e32 v160, v160, v162
	v_mul_f32_e32 v161, v161, v163
	v_cvt_pk_bf16_f32 v160, v160, v161
	global_store_dword v180, v160, s[92:93]

.LfxA_done:
	v_mov_b32_e32 v8, v230
	s_cmpk_lt_i32 s84, 0x100
	s_cselect_b64 s[4:5], -1, 0
	s_cmpk_gt_i32 s84, 0xff
	v_readfirstlane_b32 s8, v8
	s_cbranch_scc1 .LBB0_1104
	v_readlane_b32 s6, v255, 0
	v_readlane_b32 s7, v255, 1
	s_and_b64 vcc, exec, s[6:7]
	s_cbranch_vccz .LBB0_1101
	v_readlane_b32 s0, v254, 51
	s_lshl_b32 s0, s0, 5
	s_cbranch_execz .LBB0_1102
	s_branch .LBB0_1103

.LBB0_1934:
	s_cmp_gt_i32 s72, 21
	s_cselect_b64 s[0:1], -1, 0
	s_cmp_lt_i32 s73, 22
	s_cselect_b64 s[4:5], -1, 0
	s_or_b64 s[0:1], s[0:1], s[4:5]
	s_and_b64 vcc, exec, s[0:1]
	s_cbranch_vccnz .LBB0_1992
	s_branch .LBB0_1992
	v_mov_b32_e32 v0, v230
	v_readlane_b32 s0, v254, 55
	s_nop 1
	v_add_u32_e32 v160, s0, v0
	s_mov_b32 s0, 0x58000
	v_cmp_gt_i32_e32 vcc, s0, v160
	s_and_saveexec_b64 s[4:5], vcc
	s_cbranch_execz .LBB0_1942
	s_add_u32 s6, s70, 0x3b00000
	s_addc_u32 s7, s71, 0
	v_readlane_b32 s20, v254, 3
	s_add_u32 s8, s70, 0xbf00000
	v_readlane_b32 s22, v254, 5
	v_readlane_b32 s23, v254, 6
	s_addc_u32 s9, s71, 0
	s_mov_b64 s[38:39], s[22:23]
	v_readlane_b32 s24, v254, 7
	v_readlane_b32 s25, v254, 8
	s_add_u32 s10, s38, 0x10800
	s_mov_b64 s[40:41], s[24:25]
	s_addc_u32 s11, s39, 0
	s_add_u32 s12, s40, 0x5800
	s_addc_u32 s13, s41, 0
	s_add_u32 s14, s40, 0x8400
	s_addc_u32 s15, s41, 0
	s_add_u32 s16, s38, 0x13400
	s_addc_u32 s17, s39, 0
	s_add_u32 s22, s38, 0x16000
	s_addc_u32 s23, s39, 0
	s_add_u32 s24, s38, 0x18c00
	v_readlane_b32 s26, v254, 9
	s_addc_u32 s25, s39, 0
	v_readlane_b32 s27, v254, 10
	s_add_u32 s26, s38, 0x1b800
	s_addc_u32 s27, s39, 0
	s_add_u32 s28, s38, 0x1e400
	v_lshlrev_b32_e32 v0, 3, v0
	s_addc_u32 s29, s39, 0
	v_lshl_add_u32 v161, s84, 12, v0
	s_lshl_b32 s0, s97, 3
	s_mov_b64 s[30:31], 0
	s_mov_b32 s1, 0x2e8ba2e9
	s_movk_i32 s33, 0x2c00
	s_movk_i32 s35, 0x3f8
	v_mov_b64_e32 v[144:145], s[6:7]
	s_mov_b32 s34, 0xbfb8aa3b
	s_movk_i32 s36, 0x1600
	s_mov_b32 s37, 0x57fff
	v_readlane_b32 s21, v254, 4
	s_branch .LBB0_1938

.LBB0_1992:
	s_cmp_lt_i32 s72, 23
	s_cselect_b64 s[0:1], -1, 0
	s_cmp_gt_i32 s73, 22
	s_cselect_b64 s[4:5], -1, 0
	s_and_b64 s[0:1], s[0:1], s[4:5]
	s_and_b64 vcc, exec, s[0:1]
	s_cbranch_vccz .LBB0_2025
	s_cmpk_gt_i32 s84, 0xff
	s_cbranch_scc1 .LfxB_done
	s_and_b32 s6, s84, 7
	s_lshl_b32 s6, s6, 3
	s_bfe_u32 s7, s84, 0x30003
	s_add_i32 s4, s6, s7
	s_sub_i32 s4, s4, 32
	s_cmp_lt_i32 s4, 0
	s_cbranch_scc1 .LfxB_done
	s_and_b32 s6, s4, 3
	s_cmp_lg_u32 s6, 0
	s_cselect_b32 s20, 1, 0
	s_cmp_lg_u32 s6, 3
	s_cselect_b32 s21, 1, 0
	s_add_u32 s8, s70, 0x5b00000
	s_addc_u32 s9, s71, 0
	v_readlane_b32 s10, v254, 5
	v_readlane_b32 s11, v254, 6
	s_nop 0
	s_mul_i32 s6, s4, 0x16000
	s_add_i32 s6, s6, 0x5800
	s_add_u32 s60, s8, s6
	s_addc_u32 s61, s9, 0
	s_add_i32 s6, s4, -1
	s_mul_i32 s6, s6, 0x16000
	s_add_i32 s6, s6, 0xb000
	s_add_u32 s62, s8, s6
	s_addc_u32 s63, s9, 0
	s_add_u32 s64, s10, 0x10800
	s_addc_u32 s65, s11, 0
	s_lshl_b32 s6, s4, 8
	s_mul_i32 s6, s6, 0x1600
	s_add_u32 s6, s6, 0xbf00000
	s_add_u32 s66, s70, s6
	s_addc_u32 s67, s71, 0
	s_mul_i32 s6, s4, 0x16000
	s_add_i32 s6, s6, 0x10800
	s_add_u32 s86, s8, s6
	s_addc_u32 s87, s9, 0
	s_add_i32 s6, s4, 1
	s_mul_i32 s6, s6, 0x16000
	s_add_u32 s88, s8, s6
	s_addc_u32 s89, s9, 0
	s_add_u32 s90, s10, 0x1b800
	s_addc_u32 s91, s11, 0
	s_lshl_b32 s6, s4, 8
	s_add_i32 s6, s6, 255
	s_mul_i32 s6, s6, 0x1600
	s_add_u32 s6, s6, 0xbf00000
	s_add_u32 s92, s70, s6
	s_addc_u32 s93, s71, 0
	v_readfirstlane_b32 s7, v230
	s_cmpk_lt_u32 s7, 0x180
	s_cselect_b32 s5, 1, 0
	v_lshlrev_b32_e32 v172, 3, v230
	v_add_u32_e32 v173, 0x1000, v172
	v_add_u32_e32 v174, 0x2000, v172
	v_add_u32_e32 v175, 0x2c00, v172
	v_add_u32_e32 v176, 0x2c00, v173
	v_add_u32_e32 v177, 0x2c00, v174
	v_lshlrev_b32_e32 v178, 2, v230
	v_add_u32_e32 v179, 0x800, v178
	v_add_u32_e32 v180, 0x1000, v178
	s_cmp_eq_u32 s20, 0
	s_cbranch_scc1 .LfxB_L0
	global_load_dwordx2 v[100:101], v172, s[60:61]
	global_load_dwordx2 v[102:103], v175, s[60:61]
	global_load_dwordx2 v[104:105], v172, s[62:63]
	global_load_dwordx2 v[106:107], v175, s[62:63]
	global_load_dwordx2 v[108:109], v172, s[64:65]
	global_load_dwordx2 v[110:111], v175, s[64:65]
	global_load_dwordx2 v[112:113], v173, s[60:61]
	global_load_dwordx2 v[114:115], v176, s[60:61]
	global_load_dwordx2 v[116:117], v173, s[62:63]
	global_load_dwordx2 v[118:119], v176, s[62:63]
	global_load_dwordx2 v[120:121], v173, s[64:65]
	global_load_dwordx2 v[122:123], v176, s[64:65]
	s_cmp_eq_u32 s5, 0
	s_cbranch_scc1 .LfxB_L0
	global_load_dwordx2 v[124:125], v174, s[60:61]
	global_load_dwordx2 v[126:127], v177, s[60:61]
	global_load_dwordx2 v[128:129], v174, s[62:63]
	global_load_dwordx2 v[130:131], v177, s[62:63]
	global_load_dwordx2 v[132:133], v174, s[64:65]
	global_load_dwordx2 v[134:135], v177, s[64:65]

.LfxB_done:
	s_cmpk_gt_i32 s84, 0xff
	v_readfirstlane_b32 s4, v230
	s_cbranch_scc1 .LBB0_2025
	v_readlane_b32 s0, v255, 0
	v_readlane_b32 s1, v255, 1
	s_and_b64 vcc, exec, s[0:1]
	s_cbranch_vccz .LBB0_1996
	v_readlane_b32 s0, v254, 51
	s_lshl_b32 s5, s0, 5
	s_cbranch_execz .LBB0_1997
	s_branch .LBB0_1998
